# attention loop head shifted by 2 s_nop (code placement test)
# speedup vs baseline: 1.0004x; 1.0004x over previous
; #define SBAR() __builtin_amdgcn_sched_barrier(0)
; __device__ __forceinline__ s16x4 vtr(lds_cptr p){ return __builtin_bit_cast(s16x4,__builtin_amdgcn_ds_read_tr16_b64_v4i16((__attribute__((address_space(3))) v4i16_t*)p)); }
;   #define DMA_K(t,s3) glds16(ksrc+(long)(t)*KVBLK*DM,(unsigned)__builtin_amdgcn_readfirstlane(kdst+(s3)*SLOTB))
;   #define DMA_V(t,s3) do{ const unsigned vd_=(unsigned)__builtin_amdgcn_readfirstlane(vdst+(s3)*VSLOTB); glds16(vsrc+(long)(t)*KVBLK*DM,vd_); glds16(vsrc+(long)(t)*KVBLK*DM+64,(unsigned)__builtin_amdgcn_readfirstlane(vd_+8192)); }while(0)
; template<int THRL> __device__ __forceinline__ void attn_unit(int qb,const bf16*Q,const bf16*__restrict__ K,const bf16*__restrict__ V,bf16*O,char*shm){
;     ...
;   for(int t=0;t<NT;++t){
;     if(t+2<NT){DMA_K(t+2,c2);DMA_V(t+2,c2);}
;     bf16x8 kf[8]; kload8(kf,kp0+c0*SLOTB);
;     SBAR();
;     f32x16 C0,C1;
;     {
;       C0=__builtin_amdgcn_mfma_f32_32x32x16_bf16(kf[0],qr[0],negm,0,0,0); C1=__builtin_amdgcn_mfma_f32_32x32x16_bf16(kf[1],qr[0],negm,0,0,0);
;       C0=__builtin_amdgcn_mfma_f32_32x32x16_bf16(kf[2],qr[1],C0,0,0,0);   C1=__builtin_amdgcn_mfma_f32_32x32x16_bf16(kf[3],qr[1],C1,0,0,0);
;       C0=__builtin_amdgcn_mfma_f32_32x32x16_bf16(kf[4],qr[2],C0,0,0,0);   C1=__builtin_amdgcn_mfma_f32_32x32x16_bf16(kf[5],qr[2],C1,0,0,0);
;       C0=__builtin_amdgcn_mfma_f32_32x32x16_bf16(kf[6],qr[3],C0,0,0,0);   C1=__builtin_amdgcn_mfma_f32_32x32x16_bf16(kf[7],qr[3],C1,0,0,0); }
;     SBAR();
;     const lds_cptr vp_=vp0+c0*VSLOTB; s16x4 vl_[8],vh_[8];
;     #pragma unroll
;     for(int k2=0;k2<2;++k2)
;       #pragma unroll
;       for(int d_=0;d_<4;++d_){ vl_[d_*2+k2]=vtr(vp_+(d_*4096+k2*1024)); vh_[d_*2+k2]=vtr(vp_+(d_*4096+k2*1024+512)); }
;     SBAR();
;     { const int jb_=t-(NT-4); if(jb_>=0)cmask(C0,C1,jb_,qrel,hi); }
.LBB0_366:
	s_lshl_b32 s14, s34, 14
	v_add_u32_e32 v193, s14, v190
	s_nop 0
	s_nop 0
.Lattn_top:
	v_mfma_f32_32x32x16_bf16 v[80:95], v[236:239], v[112:115], v[64:79]
	ds_read_b64_tr_b16 v[156:157], v193 offset:24576
	ds_read_b64_tr_b16 v[158:159], v193 offset:25088
	v_mfma_f32_32x32x16_bf16 v[80:95], v[240:243], v[116:119], v[80:95]
	ds_read_b64_tr_b16 v[140:141], v193 offset:25600
	ds_read_b64_tr_b16 v[142:143], v193 offset:26112
	v_mfma_f32_32x32x16_bf16 v[80:95], v[244:247], v[120:123], v[80:95]
	ds_read_b64_tr_b16 v[152:153], v193 offset:28672
	ds_read_b64_tr_b16 v[154:155], v193 offset:29184
	v_mfma_f32_32x32x16_bf16 v[80:95], v[248:251], v[124:127], v[80:95]
	ds_read_b64_tr_b16 v[136:137], v193 offset:29696
	ds_read_b64_tr_b16 v[138:139], v193 offset:30208
	v_mfma_f32_32x32x16_bf16 v[96:111], v[128:131], v[112:115], v[64:79]
	ds_read_b64_tr_b16 v[148:149], v193 offset:32768
	ds_read_b64_tr_b16 v[150:151], v193 offset:33280
	v_mfma_f32_32x32x16_bf16 v[96:111], v[132:135], v[116:119], v[96:111]
	ds_read_b64_tr_b16 v[132:133], v193 offset:33792
	ds_read_b64_tr_b16 v[134:135], v193 offset:34304
	v_mfma_f32_32x32x16_bf16 v[96:111], v[144:147], v[120:123], v[96:111]
	ds_read_b64_tr_b16 v[144:145], v193 offset:36864
	ds_read_b64_tr_b16 v[146:147], v193 offset:37376
	v_mfma_f32_32x32x16_bf16 v[96:111], v[194:197], v[124:127], v[96:111]
	ds_read_b64_tr_b16 v[128:129], v193 offset:37888
	ds_read_b64_tr_b16 v[130:131], v193 offset:38400
	s_add_i32 s14, s28, s31
	s_cmp_lt_i32 s14, -4
	s_cbranch_scc1 .LBB0_368
	v_subrev_u32_e32 v163, 27, v192
	v_subrev_u32_e32 v162, 59, v192
	v_cmp_le_i32_e32 vcc, v163, v188
	s_nop 5
	v_cndmask_b32_e32 v96, v229, v96, vcc
	v_cmp_lt_i32_e32 vcc, v162, v188
	s_nop 1
	v_cndmask_b32_e32 v81, v229, v81, vcc
	v_cmp_le_i32_e32 vcc, v162, v188
	v_subrev_u32_e32 v162, 26, v192
	s_nop 0
	v_cndmask_b32_e32 v80, v229, v80, vcc
	v_cmp_le_i32_e32 vcc, v162, v188
	v_subrev_u32_e32 v162, 57, v192
	s_nop 0
	v_cndmask_b32_e32 v97, v229, v97, vcc
	v_cmp_le_i32_e32 vcc, v162, v188
	v_subrev_u32_e32 v162, 25, v192
	s_nop 0
	v_cndmask_b32_e32 v82, v229, v82, vcc
	v_cmp_le_i32_e32 vcc, v162, v188
	v_subrev_u32_e32 v162, 56, v192
	s_nop 0
	v_cndmask_b32_e32 v98, v229, v98, vcc
	v_cmp_le_i32_e32 vcc, v162, v188
	v_subrev_u32_e32 v162, 24, v192
	s_nop 0
	v_cndmask_b32_e32 v83, v229, v83, vcc
	v_cmp_le_i32_e32 vcc, v162, v188
	v_subrev_u32_e32 v162, 51, v192
	s_nop 0
	v_cndmask_b32_e32 v99, v229, v99, vcc
	v_cmp_le_i32_e32 vcc, v162, v188
	v_subrev_u32_e32 v162, 19, v192
	s_nop 0
	v_cndmask_b32_e32 v84, v229, v84, vcc
	v_cmp_le_i32_e32 vcc, v162, v188
	v_subrev_u32_e32 v162, 50, v192
	s_nop 0
	v_cndmask_b32_e32 v100, v229, v100, vcc
	v_cmp_le_i32_e32 vcc, v162, v188
	v_subrev_u32_e32 v162, 18, v192
	s_nop 0
	v_cndmask_b32_e32 v85, v229, v85, vcc
	v_cmp_le_i32_e32 vcc, v162, v188
	v_subrev_u32_e32 v162, 49, v192
	s_nop 0
	v_cndmask_b32_e32 v101, v229, v101, vcc
	v_cmp_le_i32_e32 vcc, v162, v188
	v_subrev_u32_e32 v162, 17, v192
	s_nop 0
	v_cndmask_b32_e32 v86, v229, v86, vcc
	v_cmp_le_i32_e32 vcc, v162, v188
	v_subrev_u32_e32 v162, 48, v192
	s_nop 0
	v_cndmask_b32_e32 v102, v229, v102, vcc
	v_cmp_le_i32_e32 vcc, v162, v188
	v_add_u32_e32 v162, -16, v192
	s_nop 0
	v_cndmask_b32_e32 v87, v229, v87, vcc
	v_cmp_le_i32_e32 vcc, v162, v188
	v_subrev_u32_e32 v162, 43, v192
	s_nop 0
	v_cndmask_b32_e32 v103, v229, v103, vcc
	v_cmp_le_i32_e32 vcc, v162, v188
	v_add_u32_e32 v162, -11, v192
	s_nop 0
	v_cndmask_b32_e32 v88, v229, v88, vcc
	v_cmp_le_i32_e32 vcc, v162, v188
	v_subrev_u32_e32 v162, 42, v192
	s_nop 0
	v_cndmask_b32_e32 v104, v229, v104, vcc
	v_cmp_le_i32_e32 vcc, v162, v188
	v_add_u32_e32 v162, -10, v192
	s_nop 0
	v_cndmask_b32_e32 v89, v229, v89, vcc
	v_cmp_le_i32_e32 vcc, v162, v188
	v_subrev_u32_e32 v162, 41, v192
	s_nop 0
	v_cndmask_b32_e32 v105, v229, v105, vcc
	v_cmp_le_i32_e32 vcc, v162, v188
	v_add_u32_e32 v162, -9, v192
	s_nop 0
	v_cndmask_b32_e32 v90, v229, v90, vcc
	v_cmp_le_i32_e32 vcc, v162, v188
	v_subrev_u32_e32 v162, 40, v192
	s_nop 0
	v_cndmask_b32_e32 v106, v229, v106, vcc
	v_cmp_le_i32_e32 vcc, v162, v188
	v_add_u32_e32 v162, -8, v192
	s_nop 0
	v_cndmask_b32_e32 v91, v229, v91, vcc
	v_cmp_le_i32_e32 vcc, v162, v188
	v_subrev_u32_e32 v162, 35, v192
	s_nop 0
	v_cndmask_b32_e32 v107, v229, v107, vcc
	v_cmp_le_i32_e32 vcc, v162, v188
	v_add_u32_e32 v162, -3, v192
	s_nop 0
	v_cndmask_b32_e32 v92, v229, v92, vcc
	v_cmp_le_i32_e32 vcc, v162, v188
	v_subrev_u32_e32 v162, 34, v192
	s_nop 0
	v_cndmask_b32_e32 v108, v229, v108, vcc
	v_cmp_le_i32_e32 vcc, v162, v188
	v_add_u32_e32 v162, -2, v192
	s_nop 0
	v_cndmask_b32_e32 v93, v229, v93, vcc
	v_cmp_le_i32_e32 vcc, v162, v188
	v_subrev_u32_e32 v162, 33, v192
	s_nop 0
	v_cndmask_b32_e32 v109, v229, v109, vcc
	v_cmp_le_i32_e32 vcc, v162, v188
	v_add_u32_e32 v162, -1, v192
	s_nop 0
	v_cndmask_b32_e32 v94, v229, v94, vcc
	v_cmp_le_i32_e32 vcc, v162, v188
	v_subrev_u32_e32 v162, 32, v192
	s_nop 0
	v_cndmask_b32_e32 v110, v229, v110, vcc
	v_cmp_le_i32_e32 vcc, v162, v188
	s_nop 1
	v_cndmask_b32_e32 v95, v229, v95, vcc
	v_cmp_le_i32_e32 vcc, v192, v188
	s_nop 1
	v_cndmask_b32_e32 v111, v229, v111, vcc
